# v2 plus: nt loads for all x rows in the prologue rmsnorm
# speedup vs baseline: 1.0499x; 1.0124x over previous
.LBB0_64:
	v_readlane_b32 s0, v249, 4
	s_lshl_b32 s2, s0, 11
	v_readlane_b32 s0, v249, 3
	s_lshl_b32 s0, s0, 8
	v_readlane_b32 s1, v249, 0
	s_and_b32 s3, s0, 0x700
	s_and_b32 s0, s18, 0xffffffc0
	s_lshl_b32 s1, s1, 3
	s_add_i32 s4, s0, s1
	s_load_dwordx2 s[0:1], s[16:17], 0x0
	s_add_i32 s2, s4, s2
	s_add_i32 s2, s2, s3
	s_ashr_i32 s3, s2, 31
	s_lshl_b64 s[4:5], s[2:3], 12
	s_waitcnt lgkmcnt(0)
	s_add_u32 s0, s0, s4
	s_addc_u32 s1, s1, s5
	v_lshlrev_b32_e32 v106, 4, v108
	v_mov_b32_e32 v107, 0
	global_load_dwordx4 v[102:105], v106, s[0:1] nt
	global_load_dwordx4 v[98:101], v106, s[0:1] offset:1024 nt
	global_load_dwordx4 v[94:97], v106, s[0:1] offset:2048 nt
	global_load_dwordx4 v[78:81], v106, s[0:1] offset:3072 nt
	v_lshl_add_u64 v[50:51], s[0:1], 0, v[106:107]
	s_movk_i32 s1, 0x2000
	v_add_co_u32_e32 v54, vcc, s1, v50
	s_movk_i32 s0, 0x1000
	s_nop 0
	v_addc_co_u32_e32 v55, vcc, 0, v51, vcc
	global_load_dwordx4 v[86:89], v[54:55], off offset:-4096 nt
	v_add_co_u32_e32 v2, vcc, s0, v50
	s_movk_i32 s4, 0x3000
	s_nop 0
	v_addc_co_u32_e32 v3, vcc, 0, v51, vcc
	global_load_dwordx4 v[66:69], v[2:3], off offset:1024 nt
	global_load_dwordx4 v[42:45], v[2:3], off offset:2048 nt
	global_load_dwordx4 v[34:37], v[2:3], off offset:3072 nt
	v_add_co_u32_e32 v56, vcc, s4, v50
	s_movk_i32 s5, 0x4000
	s_nop 0
	v_addc_co_u32_e32 v57, vcc, 0, v51, vcc
	v_add_co_u32_e32 v52, vcc, s5, v50
	s_movk_i32 s6, 0x7000
	s_nop 0
	v_addc_co_u32_e32 v53, vcc, 0, v51, vcc
	v_add_co_u32_e32 v110, vcc, s6, v50
	s_lshl_b64 s[0:1], s[2:3], 11
	s_nop 0
	v_addc_co_u32_e32 v111, vcc, 0, v51, vcc
	global_load_dwordx4 v[46:49], v[54:55], off nt
	global_load_dwordx4 v[38:41], v[54:55], off offset:1024 nt
	global_load_dwordx4 v[30:33], v[54:55], off offset:2048 nt
	global_load_dwordx4 v[26:29], v[54:55], off offset:3072 nt
	global_load_dwordx4 v[18:21], v[56:57], off offset:1024 nt
	global_load_dwordx4 v[14:17], v[56:57], off offset:2048 nt
	global_load_dwordx4 v[10:13], v[56:57], off offset:3072 nt
	global_load_dwordx4 v[22:25], v[52:53], off offset:-4096 nt
	global_load_dwordx4 v[6:9], v[52:53], off nt
	global_load_dwordx4 v[2:5], v[110:111], off offset:3072 nt
	s_movk_i32 s2, 0x5000
	global_load_dwordx4 v[74:77], v[52:53], off offset:1024 nt
	global_load_dwordx4 v[62:65], v[52:53], off offset:2048 nt
	s_add_u32 s0, s10, s0
	s_addc_u32 s1, s11, s1
	s_waitcnt vmcnt(19)
	v_mul_f32_e32 v1, v103, v103
	v_mul_f32_e32 v54, v105, v105
	s_waitcnt vmcnt(18)
	v_mul_f32_e32 v55, v99, v99
	v_mul_f32_e32 v56, v101, v101
	s_waitcnt vmcnt(17)
	v_mul_f32_e32 v57, v95, v95
	v_mul_f32_e32 v58, v97, v97
	s_waitcnt vmcnt(16)
	v_mul_f32_e32 v59, v79, v79
	v_mul_f32_e32 v60, v81, v81
	v_fmac_f32_e32 v1, v102, v102
	v_fmac_f32_e32 v54, v104, v104
	v_fmac_f32_e32 v55, v98, v98
	v_fmac_f32_e32 v56, v100, v100
	v_fmac_f32_e32 v57, v94, v94
	v_fmac_f32_e32 v58, v96, v96
	v_fmac_f32_e32 v59, v78, v78
	v_fmac_f32_e32 v60, v80, v80
	v_add_f32_e32 v1, v1, v54
	v_add_f32_e32 v54, v55, v56
	v_add_f32_e32 v55, v57, v58
	v_add_f32_e32 v56, v59, v60
	s_waitcnt vmcnt(15)
	v_mul_f32_e32 v57, v87, v87
	v_mul_f32_e32 v58, v89, v89
	s_waitcnt vmcnt(14)
	v_mul_f32_e32 v59, v67, v67
	v_mul_f32_e32 v60, v69, v69
	v_add_f32_e32 v1, v1, v54
	v_fmac_f32_e32 v57, v86, v86
	v_fmac_f32_e32 v58, v88, v88
	v_fmac_f32_e32 v59, v66, v66
	v_fmac_f32_e32 v60, v68, v68
	v_add_f32_e32 v1, v1, v55
	v_add_f32_e32 v54, v57, v58
	v_add_f32_e32 v55, v59, v60
	v_add_f32_e32 v1, v1, v56
	v_add_f32_e32 v54, v54, v55
	s_waitcnt vmcnt(13)
	v_mul_f32_e32 v55, v43, v43
	v_mul_f32_e32 v56, v45, v45
	v_fmac_f32_e32 v55, v42, v42
	v_fmac_f32_e32 v56, v44, v44
	v_add_f32_e32 v55, v55, v56
	v_mbcnt_lo_u32_b32 v56, -1, 0
	v_mbcnt_hi_u32_b32 v56, -1, v56
	v_and_b32_e32 v57, 64, v56
	v_add_u32_e32 v57, 64, v57
	v_xor_b32_e32 v58, 1, v56
	v_cmp_lt_i32_e32 vcc, v58, v57
	v_add_f32_e32 v54, v54, v55
	s_waitcnt vmcnt(12)
	v_mul_f32_e32 v55, v35, v35
	v_cndmask_b32_e32 v58, v56, v58, vcc
	v_lshlrev_b32_e32 v113, 2, v58
	ds_bpermute_b32 v58, v113, v1
	v_mul_f32_e32 v59, v37, v37
	v_fmac_f32_e32 v55, v34, v34
	v_fmac_f32_e32 v59, v36, v36
	v_add_f32_e32 v55, v55, v59
	s_waitcnt lgkmcnt(0)
	v_add_f32_e32 v1, v1, v58
	v_xor_b32_e32 v58, 2, v56
	v_cmp_lt_i32_e32 vcc, v58, v57
	v_add_f32_e32 v54, v54, v55
	ds_bpermute_b32 v55, v113, v54
	v_cndmask_b32_e32 v58, v56, v58, vcc
	v_lshlrev_b32_e32 v120, 2, v58
	ds_bpermute_b32 v58, v120, v1
	s_waitcnt lgkmcnt(1)
	v_add_f32_e32 v54, v54, v55
	ds_bpermute_b32 v55, v120, v54
	s_waitcnt lgkmcnt(1)
	v_add_f32_e32 v1, v1, v58
	v_xor_b32_e32 v58, 4, v56
	v_cmp_lt_i32_e32 vcc, v58, v57
	s_waitcnt lgkmcnt(0)
	v_add_f32_e32 v54, v54, v55
	v_cndmask_b32_e32 v58, v56, v58, vcc
	v_lshlrev_b32_e32 v121, 2, v58
	ds_bpermute_b32 v58, v121, v1
	v_add_co_u32_e32 v114, vcc, s2, v50
	ds_bpermute_b32 v55, v121, v54
	s_nop 0
	v_addc_co_u32_e32 v115, vcc, 0, v51, vcc
	s_waitcnt lgkmcnt(1)
	v_add_f32_e32 v1, v1, v58
	v_xor_b32_e32 v58, 8, v56
	v_cmp_lt_i32_e32 vcc, v58, v57
	s_movk_i32 s2, 0x6000
	s_nop 0
	v_cndmask_b32_e32 v58, v56, v58, vcc
	v_lshlrev_b32_e32 v122, 2, v58
	ds_bpermute_b32 v58, v122, v1
	v_add_co_u32_e32 v116, vcc, s2, v50
	s_waitcnt lgkmcnt(1)
	v_add_f32_e32 v50, v54, v55
	v_addc_co_u32_e32 v117, vcc, 0, v51, vcc
	s_waitcnt lgkmcnt(0)
	v_add_f32_e32 v51, v1, v58
	v_xor_b32_e32 v1, 16, v56
	ds_bpermute_b32 v54, v122, v50
	v_cmp_lt_i32_e32 vcc, v1, v57
	global_load_dwordx4 v[90:93], v[52:53], off offset:3072 nt
	global_load_dwordx4 v[82:85], v[116:117], off offset:-4096 nt
	global_load_dwordx4 v[70:73], v[114:115], off offset:1024 nt
	global_load_dwordx4 v[58:61], v[114:115], off offset:2048 nt
	v_cndmask_b32_e32 v1, v56, v1, vcc
	v_lshlrev_b32_e32 v1, 2, v1
	ds_bpermute_b32 v55, v1, v51
	s_waitcnt lgkmcnt(1)
	v_add_f32_e32 v106, v50, v54
	v_xor_b32_e32 v50, 32, v56
	v_cmp_lt_i32_e32 vcc, v50, v57
	ds_bpermute_b32 v112, v1, v106
	s_waitcnt lgkmcnt(1)
	v_add_f32_e32 v109, v51, v55
	v_cndmask_b32_e32 v50, v56, v50, vcc
	v_lshlrev_b32_e32 v233, 2, v50
	ds_bpermute_b32 v118, v233, v109
	s_waitcnt lgkmcnt(1)
	v_add_f32_e32 v106, v106, v112
	v_mov_b32_e32 v112, 0x358637bd
	ds_bpermute_b32 v119, v233, v106
	global_load_dwordx4 v[54:57], v[116:117], off nt
	global_load_dwordx4 v[50:53], v[116:117], off offset:1024 nt
	s_waitcnt lgkmcnt(1)
	v_add_f32_e32 v109, v109, v118
	v_fmamk_f32 v109, v109, 0x3a800000, v112
	v_rsq_f32_e32 v123, v109
	s_waitcnt lgkmcnt(0)
	v_add_f32_e32 v124, v106, v119
	v_lshlrev_b32_e32 v106, 3, v108
	v_lshl_add_u64 v[106:107], s[0:1], 0, v[106:107]
	v_mul_f32_e32 v102, v102, v123
	v_mul_f32_e32 v103, v103, v123
	v_bfe_u32 v108, v102, 16, 1
	s_movk_i32 s0, 0x7fff
	v_add3_u32 v102, v102, v108, s0
	v_bfe_u32 v108, v103, 16, 1
	v_lshrrev_b32_e32 v102, 16, v102
	v_add3_u32 v103, v103, v108, s0
	s_mov_b32 s1, 0xffff0000
	v_mul_f32_e32 v133, v78, v123
	v_fmamk_f32 v78, v124, 0x3a800000, v112
	v_and_or_b32 v118, v103, s1, v102
	v_mul_f32_e32 v102, v104, v123
	v_rsq_f32_e32 v124, v78
	v_mul_f32_e32 v103, v105, v123
	v_bfe_u32 v104, v102, 16, 1
	v_add3_u32 v102, v102, v104, s0
	v_bfe_u32 v104, v103, 16, 1
	v_lshrrev_b32_e32 v102, 16, v102
	v_add3_u32 v103, v103, v104, s0
	v_and_or_b32 v119, v103, s1, v102
	v_mul_f32_e32 v125, v98, v123
	v_mul_f32_e32 v126, v99, v123
	v_mul_f32_e32 v127, v100, v123
	v_mul_f32_e32 v128, v101, v123
	v_mul_f32_e32 v129, v94, v123
	v_mul_f32_e32 v130, v95, v123
	v_mul_f32_e32 v131, v96, v123
	v_mul_f32_e32 v132, v97, v123
	v_mul_f32_e32 v134, v79, v123
	v_mul_f32_e32 v135, v80, v123
	v_mul_f32_e32 v123, v81, v123
	v_mul_f32_e32 v136, v86, v124
	v_mul_f32_e32 v137, v87, v124
	v_mul_f32_e32 v138, v88, v124
	v_mul_f32_e32 v139, v89, v124
	v_mul_f32_e32 v140, v66, v124
	v_mul_f32_e32 v141, v67, v124
	v_mul_f32_e32 v142, v68, v124
	v_mul_f32_e32 v143, v69, v124
	global_load_dwordx4 v[98:101], v[116:117], off offset:2048 nt
	global_load_dwordx4 v[94:97], v[116:117], off offset:3072 nt
	global_load_dwordx4 v[102:105], v[114:115], off offset:3072 nt
	global_load_dwordx4 v[86:89], v[110:111], off nt
	global_load_dwordx4 v[78:81], v[110:111], off offset:1024 nt
	global_load_dwordx4 v[66:69], v[110:111], off offset:2048 nt
	v_bfe_u32 v110, v125, 16, 1
	v_add3_u32 v110, v125, v110, s0
	v_bfe_u32 v111, v126, 16, 1
	v_bfe_u32 v114, v127, 16, 1
	s_mov_b32 s2, 0x3001000
	v_add3_u32 v111, v126, v111, s0
	v_add3_u32 v115, v127, v114, s0
	v_bfe_u32 v114, v128, 16, 1
	v_lshrrev_b32_e32 v110, 16, v110
	v_add_co_u32_e32 v108, vcc, s2, v106
	v_add3_u32 v116, v128, v114, s0
	v_and_or_b32 v114, v111, s1, v110
	v_lshrrev_b32_e32 v110, 16, v115
	s_mov_b64 s[2:3], 0x3000000
	v_and_or_b32 v115, v116, s1, v110
	v_lshl_add_u64 v[110:111], v[106:107], 0, s[2:3]
	global_store_dwordx2 v[110:111], v[114:115], off offset:512
	v_bfe_u32 v114, v129, 16, 1
	v_add3_u32 v114, v129, v114, s0
	v_bfe_u32 v115, v130, 16, 1
	v_bfe_u32 v116, v131, 16, 1
	v_add3_u32 v115, v130, v115, s0
	v_add3_u32 v116, v131, v116, s0
	v_bfe_u32 v117, v132, 16, 1
	v_lshrrev_b32_e32 v114, 16, v114
	v_add3_u32 v117, v132, v117, s0
	v_and_or_b32 v114, v115, s1, v114
	v_lshrrev_b32_e32 v115, 16, v116
	v_and_or_b32 v115, v117, s1, v115
	global_store_dwordx2 v[110:111], v[114:115], off offset:1024
	v_bfe_u32 v114, v133, 16, 1
	v_add3_u32 v114, v133, v114, s0
	v_bfe_u32 v115, v134, 16, 1
	v_bfe_u32 v116, v135, 16, 1
	v_add3_u32 v115, v134, v115, s0
	v_add3_u32 v116, v135, v116, s0
	v_bfe_u32 v117, v123, 16, 1
	v_lshrrev_b32_e32 v114, 16, v114
	v_add3_u32 v117, v123, v117, s0
	v_and_or_b32 v114, v115, s1, v114
	v_lshrrev_b32_e32 v115, 16, v116
	v_and_or_b32 v115, v117, s1, v115
	global_store_dwordx2 v[110:111], v[114:115], off offset:1536
	v_bfe_u32 v114, v136, 16, 1
	v_add3_u32 v114, v136, v114, s0
	v_bfe_u32 v115, v137, 16, 1
	v_bfe_u32 v116, v138, 16, 1
	v_add3_u32 v115, v137, v115, s0
	v_add3_u32 v116, v138, v116, s0
	v_bfe_u32 v117, v139, 16, 1
	v_lshrrev_b32_e32 v114, 16, v114
	v_add3_u32 v117, v139, v117, s0
	v_and_or_b32 v114, v115, s1, v114
	v_lshrrev_b32_e32 v115, 16, v116
	v_and_or_b32 v115, v117, s1, v115
	global_store_dwordx2 v[110:111], v[114:115], off offset:2048
	s_waitcnt vmcnt(27)
	v_mul_f32_e32 v114, v47, v47
	v_mul_f32_e32 v115, v49, v49
	v_fmac_f32_e32 v114, v46, v46
	v_fmac_f32_e32 v115, v48, v48
	v_add_f32_e32 v114, v114, v115
	s_waitcnt vmcnt(26)
	v_mul_f32_e32 v115, v39, v39
	v_mul_f32_e32 v116, v41, v41
	v_fmac_f32_e32 v115, v38, v38
	v_fmac_f32_e32 v116, v40, v40
	v_add_f32_e32 v115, v115, v116
	v_add_f32_e32 v114, v114, v115
	s_waitcnt vmcnt(25)
	v_mul_f32_e32 v115, v31, v31
	v_mul_f32_e32 v116, v33, v33
	v_fmac_f32_e32 v115, v30, v30
	v_fmac_f32_e32 v116, v32, v32
	v_add_f32_e32 v115, v115, v116
	v_add_f32_e32 v114, v114, v115
	s_waitcnt vmcnt(24)
	v_mul_f32_e32 v115, v27, v27
	v_mul_f32_e32 v116, v29, v29
	v_fmac_f32_e32 v115, v26, v26
	v_fmac_f32_e32 v116, v28, v28
	v_add_f32_e32 v115, v115, v116
	v_add_f32_e32 v114, v114, v115
	s_waitcnt vmcnt(20)
	v_mul_f32_e32 v115, v23, v23
	v_mul_f32_e32 v116, v25, v25
	v_fmac_f32_e32 v115, v22, v22
	v_fmac_f32_e32 v116, v24, v24
	v_add_f32_e32 v115, v115, v116
	v_mul_f32_e32 v116, v19, v19
	v_mul_f32_e32 v117, v21, v21
	v_fmac_f32_e32 v116, v18, v18
	v_fmac_f32_e32 v117, v20, v20
	v_add_f32_e32 v116, v116, v117
	v_add_f32_e32 v115, v115, v116
	v_mul_f32_e32 v116, v15, v15
	v_mul_f32_e32 v117, v17, v17
	v_fmac_f32_e32 v116, v14, v14
	v_fmac_f32_e32 v117, v16, v16
	v_add_f32_e32 v116, v116, v117
	v_add_f32_e32 v115, v115, v116
	v_mul_f32_e32 v116, v11, v11
	v_mul_f32_e32 v117, v13, v13
	v_fmac_f32_e32 v116, v10, v10
	v_fmac_f32_e32 v117, v12, v12
	v_add_f32_e32 v116, v116, v117
	v_add_f32_e32 v115, v115, v116
	s_waitcnt vmcnt(19)
	v_mul_f32_e32 v116, v7, v7
	v_mul_f32_e32 v117, v9, v9
	v_addc_co_u32_e32 v109, vcc, 0, v107, vcc
	v_fmac_f32_e32 v116, v6, v6
	v_fmac_f32_e32 v117, v8, v8
	global_store_dwordx2 v[108:109], v[118:119], off offset:-4096
	v_add_f32_e32 v116, v116, v117
	s_waitcnt vmcnt(18)
	v_mul_f32_e32 v117, v75, v75
	v_mul_f32_e32 v118, v77, v77
	v_fmac_f32_e32 v117, v74, v74
	v_fmac_f32_e32 v118, v76, v76
	v_add_f32_e32 v117, v117, v118
	v_add_f32_e32 v116, v116, v117
	s_waitcnt vmcnt(17)
	v_mul_f32_e32 v117, v63, v63
	v_mul_f32_e32 v118, v65, v65
	v_fmac_f32_e32 v117, v62, v62
	v_fmac_f32_e32 v118, v64, v64
	v_add_f32_e32 v117, v117, v118
	v_add_f32_e32 v116, v116, v117
	s_waitcnt vmcnt(16)
	v_mul_f32_e32 v117, v91, v91
	v_mul_f32_e32 v118, v93, v93
	v_fmac_f32_e32 v117, v90, v90
	v_fmac_f32_e32 v118, v92, v92
	v_add_f32_e32 v117, v117, v118
	v_add_f32_e32 v116, v116, v117
	s_waitcnt vmcnt(15)
	v_mul_f32_e32 v117, v83, v83
	v_mul_f32_e32 v118, v85, v85
	v_fmac_f32_e32 v117, v82, v82
	v_fmac_f32_e32 v118, v84, v84
	v_add_f32_e32 v117, v117, v118
	s_waitcnt vmcnt(14)
	v_mul_f32_e32 v118, v71, v71
	v_mul_f32_e32 v119, v73, v73
	v_fmac_f32_e32 v118, v70, v70
	v_fmac_f32_e32 v119, v72, v72
	v_add_f32_e32 v118, v118, v119
	v_add_f32_e32 v117, v117, v118
	s_waitcnt vmcnt(13)
	v_mul_f32_e32 v118, v59, v59
	v_mul_f32_e32 v119, v61, v61
	v_fmac_f32_e32 v118, v58, v58
	v_fmac_f32_e32 v119, v60, v60
	v_add_f32_e32 v118, v118, v119
	v_add_f32_e32 v117, v117, v118
	s_waitcnt vmcnt(8)
	v_mul_f32_e32 v118, v103, v103
	v_mul_f32_e32 v119, v105, v105
	v_fmac_f32_e32 v118, v102, v102
	v_fmac_f32_e32 v119, v104, v104
	v_add_f32_e32 v118, v118, v119
	v_add_f32_e32 v117, v117, v118
	v_mul_f32_e32 v118, v55, v55
	v_mul_f32_e32 v119, v57, v57
	v_fmac_f32_e32 v118, v54, v54
	v_fmac_f32_e32 v119, v56, v56
	v_add_f32_e32 v118, v118, v119
	v_mul_f32_e32 v119, v51, v51
	v_mul_f32_e32 v123, v53, v53
	v_fmac_f32_e32 v119, v50, v50
	v_fmac_f32_e32 v123, v52, v52
	v_add_f32_e32 v119, v119, v123
	v_add_f32_e32 v118, v118, v119
	v_mul_f32_e32 v119, v99, v99
	v_mul_f32_e32 v123, v101, v101
	v_fmac_f32_e32 v119, v98, v98
	v_fmac_f32_e32 v123, v100, v100
	v_add_f32_e32 v119, v119, v123
	v_add_f32_e32 v118, v118, v119
	v_mul_f32_e32 v119, v95, v95
	v_mul_f32_e32 v123, v97, v97
	v_fmac_f32_e32 v119, v94, v94
	v_fmac_f32_e32 v123, v96, v96
	v_add_f32_e32 v119, v119, v123
	v_add_f32_e32 v118, v118, v119
	s_waitcnt vmcnt(7)
	v_mul_f32_e32 v119, v87, v87
	v_mul_f32_e32 v123, v89, v89
	v_fmac_f32_e32 v119, v86, v86
	v_fmac_f32_e32 v123, v88, v88
	v_add_f32_e32 v119, v119, v123
	s_waitcnt vmcnt(6)
	v_mul_f32_e32 v123, v79, v79
	v_mul_f32_e32 v125, v81, v81
	v_fmac_f32_e32 v123, v78, v78
	v_fmac_f32_e32 v125, v80, v80
	v_add_f32_e32 v123, v123, v125
	v_add_f32_e32 v119, v119, v123
	s_waitcnt vmcnt(5)
	v_mul_f32_e32 v123, v67, v67
	v_mul_f32_e32 v125, v69, v69
	v_fmac_f32_e32 v123, v66, v66
	v_fmac_f32_e32 v125, v68, v68
	v_add_f32_e32 v123, v123, v125
	ds_bpermute_b32 v125, v113, v114
	v_add_f32_e32 v119, v119, v123
	v_mul_f32_e32 v123, v3, v3
	v_mul_f32_e32 v126, v5, v5
	v_fmac_f32_e32 v123, v2, v2
	v_fmac_f32_e32 v126, v4, v4
	v_add_f32_e32 v123, v123, v126
	v_add_f32_e32 v119, v119, v123
	s_waitcnt lgkmcnt(0)
	v_add_f32_e32 v114, v114, v125
	ds_bpermute_b32 v123, v113, v115
	ds_bpermute_b32 v125, v113, v116
	ds_bpermute_b32 v126, v113, v117
	ds_bpermute_b32 v127, v113, v118
	ds_bpermute_b32 v113, v113, v119
	s_waitcnt lgkmcnt(4)
	v_add_f32_e32 v115, v115, v123
	ds_bpermute_b32 v123, v120, v115
	s_waitcnt lgkmcnt(4)
	v_add_f32_e32 v116, v116, v125
	s_waitcnt lgkmcnt(3)
	v_add_f32_e32 v117, v117, v126
	s_waitcnt lgkmcnt(1)
	v_add_f32_e32 v113, v119, v113
	ds_bpermute_b32 v119, v120, v114
	v_add_f32_e32 v118, v118, v127
	ds_bpermute_b32 v125, v120, v116
	ds_bpermute_b32 v126, v120, v117
	ds_bpermute_b32 v127, v120, v118
	s_waitcnt lgkmcnt(3)
	v_add_f32_e32 v114, v114, v119
	v_add_f32_e32 v115, v115, v123
	ds_bpermute_b32 v119, v120, v113
	ds_bpermute_b32 v120, v121, v114
	ds_bpermute_b32 v123, v121, v115
	s_waitcnt lgkmcnt(5)
	v_add_f32_e32 v116, v116, v125
	s_waitcnt lgkmcnt(4)
	v_add_f32_e32 v117, v117, v126
	s_waitcnt lgkmcnt(3)
	v_add_f32_e32 v118, v118, v127
	s_waitcnt lgkmcnt(2)
	v_add_f32_e32 v113, v113, v119
	s_waitcnt lgkmcnt(1)
	v_add_f32_e32 v114, v114, v120
	ds_bpermute_b32 v125, v121, v116
	ds_bpermute_b32 v126, v121, v117
	s_waitcnt lgkmcnt(2)
	v_add_f32_e32 v115, v115, v123
	ds_bpermute_b32 v119, v121, v118
	ds_bpermute_b32 v120, v121, v113
	ds_bpermute_b32 v121, v122, v114
	ds_bpermute_b32 v123, v122, v115
	s_waitcnt lgkmcnt(5)
	v_add_f32_e32 v116, v116, v125
	s_waitcnt lgkmcnt(4)
	v_add_f32_e32 v117, v117, v126
	s_waitcnt lgkmcnt(3)
	v_add_f32_e32 v118, v118, v119
	s_waitcnt lgkmcnt(2)
	v_add_f32_e32 v113, v113, v120
	s_waitcnt lgkmcnt(1)
	v_add_f32_e32 v114, v114, v121
	ds_bpermute_b32 v125, v122, v116
	s_waitcnt lgkmcnt(1)
	v_add_f32_e32 v115, v115, v123
	ds_bpermute_b32 v119, v122, v117
	ds_bpermute_b32 v120, v122, v118
	ds_bpermute_b32 v121, v122, v113
	ds_bpermute_b32 v122, v1, v114
	ds_bpermute_b32 v123, v1, v115
	s_waitcnt lgkmcnt(5)
	v_add_f32_e32 v116, v116, v125
	s_waitcnt lgkmcnt(4)
	v_add_f32_e32 v117, v117, v119
	ds_bpermute_b32 v119, v1, v116
	s_waitcnt lgkmcnt(2)
	v_add_f32_e32 v114, v114, v122
	s_waitcnt lgkmcnt(1)
	v_add_f32_e32 v115, v115, v123
	ds_bpermute_b32 v123, v233, v114
	v_add_f32_e32 v118, v118, v120
	ds_bpermute_b32 v120, v1, v117
	v_add_f32_e32 v113, v113, v121
	ds_bpermute_b32 v121, v1, v118
	s_waitcnt lgkmcnt(3)
	v_add_f32_e32 v116, v116, v119
	s_waitcnt lgkmcnt(2)
	v_add_f32_e32 v119, v114, v123
	ds_bpermute_b32 v114, v233, v115
	s_waitcnt lgkmcnt(2)
	v_add_f32_e32 v117, v117, v120
	ds_bpermute_b32 v120, v233, v116
	s_waitcnt lgkmcnt(2)
	v_add_f32_e32 v118, v118, v121
	ds_bpermute_b32 v121, v233, v117
	s_waitcnt lgkmcnt(2)
	v_add_f32_e32 v125, v115, v114
	v_bfe_u32 v114, v140, 16, 1
	s_waitcnt lgkmcnt(1)
	v_add_f32_e32 v116, v116, v120
	v_add3_u32 v114, v140, v114, s0
	v_bfe_u32 v115, v141, 16, 1
	v_bfe_u32 v120, v142, 16, 1
	s_waitcnt lgkmcnt(0)
	v_add_f32_e32 v117, v117, v121
	v_add3_u32 v115, v141, v115, s0
	v_add3_u32 v120, v142, v120, s0
	v_bfe_u32 v121, v143, 16, 1
	v_lshrrev_b32_e32 v114, 16, v114
	v_add3_u32 v121, v143, v121, s0
	v_and_or_b32 v114, v115, s1, v114
	v_lshrrev_b32_e32 v115, 16, v120
	v_and_or_b32 v115, v121, s1, v115
	v_mul_f32_e32 v42, v42, v124
	global_store_dwordx2 v[110:111], v[114:115], off offset:2560
	v_mul_f32_e32 v43, v43, v124
	v_bfe_u32 v114, v42, 16, 1
	v_add3_u32 v42, v42, v114, s0
	v_bfe_u32 v114, v43, 16, 1
	v_lshrrev_b32_e32 v42, 16, v42
	v_add3_u32 v43, v43, v114, s0
	v_and_or_b32 v42, v43, s1, v42
	v_mul_f32_e32 v43, v44, v124
	v_mul_f32_e32 v44, v45, v124
	v_bfe_u32 v45, v43, 16, 1
	v_add3_u32 v43, v43, v45, s0
	v_bfe_u32 v45, v44, 16, 1
	v_lshrrev_b32_e32 v43, 16, v43
	v_add3_u32 v44, v44, v45, s0
	v_and_or_b32 v43, v44, s1, v43
	v_mul_f32_e32 v34, v34, v124
	global_store_dwordx2 v[110:111], v[42:43], off offset:3072
	v_mul_f32_e32 v35, v35, v124
	v_bfe_u32 v42, v34, 16, 1
	v_add3_u32 v34, v34, v42, s0
	v_bfe_u32 v42, v35, 16, 1
	v_lshrrev_b32_e32 v34, 16, v34
	v_add3_u32 v35, v35, v42, s0
	v_and_or_b32 v34, v35, s1, v34
	v_mul_f32_e32 v35, v36, v124
	v_fmamk_f32 v42, v119, 0x3a800000, v112
	v_mul_f32_e32 v36, v37, v124
	v_bfe_u32 v37, v35, 16, 1
	v_rsq_f32_e32 v42, v42
	v_add3_u32 v35, v35, v37, s0
	v_bfe_u32 v37, v36, 16, 1
	v_lshrrev_b32_e32 v35, 16, v35
	v_add3_u32 v36, v36, v37, s0
	v_and_or_b32 v35, v36, s1, v35
	global_store_dwordx2 v[110:111], v[34:35], off offset:3584
	v_mul_f32_e32 v34, v46, v42
	v_mul_f32_e32 v35, v47, v42
	v_bfe_u32 v36, v34, 16, 1
	v_add3_u32 v34, v34, v36, s0
	v_bfe_u32 v36, v35, 16, 1
	v_lshrrev_b32_e32 v34, 16, v34
	v_add3_u32 v35, v35, v36, s0
	v_and_or_b32 v34, v35, s1, v34
	v_mul_f32_e32 v35, v48, v42
	v_mul_f32_e32 v36, v49, v42
	v_bfe_u32 v37, v35, 16, 1
	v_add3_u32 v35, v35, v37, s0
	v_bfe_u32 v37, v36, 16, 1
	v_lshrrev_b32_e32 v35, 16, v35
	v_add3_u32 v36, v36, v37, s0
	v_and_or_b32 v35, v36, s1, v35
	global_store_dwordx2 v[108:109], v[34:35], off
	v_mul_f32_e32 v34, v38, v42
	v_mul_f32_e32 v35, v39, v42
	v_bfe_u32 v36, v34, 16, 1
	v_add3_u32 v34, v34, v36, s0
	v_bfe_u32 v36, v35, 16, 1
	v_lshrrev_b32_e32 v34, 16, v34
	v_add3_u32 v35, v35, v36, s0
	v_and_or_b32 v34, v35, s1, v34
	v_mul_f32_e32 v35, v40, v42
	v_mul_f32_e32 v36, v41, v42
	v_bfe_u32 v37, v35, 16, 1
	v_add3_u32 v35, v35, v37, s0
	v_bfe_u32 v37, v36, 16, 1
	v_lshrrev_b32_e32 v35, 16, v35
	v_add3_u32 v36, v36, v37, s0
	v_and_or_b32 v35, v36, s1, v35
	v_mul_f32_e32 v30, v30, v42
	global_store_dwordx2 v[108:109], v[34:35], off offset:512
	v_mul_f32_e32 v31, v31, v42
	v_bfe_u32 v34, v30, 16, 1
	v_add3_u32 v30, v30, v34, s0
	v_bfe_u32 v34, v31, 16, 1
	v_lshrrev_b32_e32 v30, 16, v30
	v_add3_u32 v31, v31, v34, s0
	v_and_or_b32 v30, v31, s1, v30
	v_mul_f32_e32 v31, v32, v42
	v_mul_f32_e32 v32, v33, v42
	v_bfe_u32 v33, v31, 16, 1
	v_add3_u32 v31, v31, v33, s0
	v_bfe_u32 v33, v32, 16, 1
	v_lshrrev_b32_e32 v31, 16, v31
	v_add3_u32 v32, v32, v33, s0
	v_and_or_b32 v31, v32, s1, v31
	v_mul_f32_e32 v26, v26, v42
	global_store_dwordx2 v[108:109], v[30:31], off offset:1024
	v_mul_f32_e32 v27, v27, v42
	v_bfe_u32 v30, v26, 16, 1
	v_add3_u32 v26, v26, v30, s0
	v_bfe_u32 v30, v27, 16, 1
	v_lshrrev_b32_e32 v26, 16, v26
	v_add3_u32 v27, v27, v30, s0
	v_fmamk_f32 v30, v125, 0x3a800000, v112
	v_and_or_b32 v26, v27, s1, v26
	v_mul_f32_e32 v27, v28, v42
	v_rsq_f32_e32 v30, v30
	v_mul_f32_e32 v28, v29, v42
	v_bfe_u32 v29, v27, 16, 1
	v_add3_u32 v27, v27, v29, s0
	v_bfe_u32 v29, v28, 16, 1
	v_lshrrev_b32_e32 v27, 16, v27
	v_add3_u32 v28, v28, v29, s0
	v_and_or_b32 v27, v28, s1, v27
	v_mul_f32_e32 v22, v22, v30
	global_store_dwordx2 v[108:109], v[26:27], off offset:1536
	v_mul_f32_e32 v23, v23, v30
	v_bfe_u32 v26, v22, 16, 1
	v_add3_u32 v22, v22, v26, s0
	v_bfe_u32 v26, v23, 16, 1
	v_lshrrev_b32_e32 v22, 16, v22
	v_add3_u32 v23, v23, v26, s0
	v_and_or_b32 v22, v23, s1, v22
	v_mul_f32_e32 v23, v24, v30
	v_mul_f32_e32 v24, v25, v30
	v_bfe_u32 v25, v23, 16, 1
	v_add3_u32 v23, v23, v25, s0
	v_bfe_u32 v25, v24, 16, 1
	v_lshrrev_b32_e32 v23, 16, v23
	v_add3_u32 v24, v24, v25, s0
	v_and_or_b32 v23, v24, s1, v23
	v_mul_f32_e32 v18, v18, v30
	global_store_dwordx2 v[108:109], v[22:23], off offset:2048
	v_mul_f32_e32 v19, v19, v30
	v_bfe_u32 v22, v18, 16, 1
	v_add3_u32 v18, v18, v22, s0
	v_bfe_u32 v22, v19, 16, 1
	v_lshrrev_b32_e32 v18, 16, v18
	v_add3_u32 v19, v19, v22, s0
	v_and_or_b32 v18, v19, s1, v18
	v_mul_f32_e32 v19, v20, v30
	v_mul_f32_e32 v20, v21, v30
	v_bfe_u32 v21, v19, 16, 1
	v_add3_u32 v19, v19, v21, s0
	v_bfe_u32 v21, v20, 16, 1
	v_lshrrev_b32_e32 v19, 16, v19
	v_add3_u32 v20, v20, v21, s0
	v_and_or_b32 v19, v20, s1, v19
	v_mul_f32_e32 v14, v14, v30
	global_store_dwordx2 v[108:109], v[18:19], off offset:2560
	v_mul_f32_e32 v15, v15, v30
	v_bfe_u32 v18, v14, 16, 1
	v_add3_u32 v14, v14, v18, s0
	v_bfe_u32 v18, v15, 16, 1
	v_lshrrev_b32_e32 v14, 16, v14
	v_add3_u32 v15, v15, v18, s0
	v_and_or_b32 v14, v15, s1, v14
	v_mul_f32_e32 v15, v16, v30
	v_mul_f32_e32 v16, v17, v30
	v_bfe_u32 v17, v15, 16, 1
	v_add3_u32 v15, v15, v17, s0
	v_bfe_u32 v17, v16, 16, 1
	v_lshrrev_b32_e32 v15, 16, v15
	v_add3_u32 v16, v16, v17, s0
	v_and_or_b32 v15, v16, s1, v15
	v_mul_f32_e32 v10, v10, v30
	global_store_dwordx2 v[108:109], v[14:15], off offset:3072
	v_mul_f32_e32 v11, v11, v30
	v_bfe_u32 v14, v10, 16, 1
	v_add3_u32 v10, v10, v14, s0
	v_bfe_u32 v14, v11, 16, 1
	v_lshrrev_b32_e32 v10, 16, v10
	v_add3_u32 v11, v11, v14, s0
	v_fmamk_f32 v14, v116, 0x3a800000, v112
	v_and_or_b32 v10, v11, s1, v10
	v_mul_f32_e32 v11, v12, v30
	v_rsq_f32_e32 v14, v14
	v_mul_f32_e32 v12, v13, v30
	v_bfe_u32 v13, v11, 16, 1
	v_add3_u32 v11, v11, v13, s0
	v_bfe_u32 v13, v12, 16, 1
	v_lshrrev_b32_e32 v11, 16, v11
	v_add3_u32 v12, v12, v13, s0
	v_and_or_b32 v11, v12, s1, v11
	v_mul_f32_e32 v6, v6, v14
	global_store_dwordx2 v[108:109], v[10:11], off offset:3584
	v_mul_f32_e32 v7, v7, v14
	v_bfe_u32 v10, v6, 16, 1
	v_add3_u32 v6, v6, v10, s0
	v_bfe_u32 v10, v7, 16, 1
	v_lshrrev_b32_e32 v6, 16, v6
	v_add3_u32 v7, v7, v10, s0
	v_and_or_b32 v10, v7, s1, v6
	v_mul_f32_e32 v6, v8, v14
	v_mul_f32_e32 v7, v9, v14
	v_bfe_u32 v8, v6, 16, 1
	v_add3_u32 v6, v6, v8, s0
	v_bfe_u32 v8, v7, 16, 1
	s_mov_b32 s2, 0x3002000
	v_add3_u32 v7, v7, v8, s0
	v_add_co_u32_e32 v8, vcc, s2, v106
	v_lshrrev_b32_e32 v6, 16, v6
	s_nop 0
	v_addc_co_u32_e32 v9, vcc, 0, v107, vcc
	s_mov_b32 s2, 0x3003000
	v_and_or_b32 v11, v7, s1, v6
	v_add_co_u32_e32 v6, vcc, s2, v106
	ds_bpermute_b32 v122, v1, v113
	s_nop 0
	v_addc_co_u32_e32 v7, vcc, 0, v107, vcc
	global_store_dwordx2 v[6:7], v[10:11], off offset:-4096
	v_mul_f32_e32 v10, v74, v14
	v_mul_f32_e32 v11, v75, v14
	v_bfe_u32 v12, v10, 16, 1
	v_add3_u32 v10, v10, v12, s0
	v_bfe_u32 v12, v11, 16, 1
	v_lshrrev_b32_e32 v10, 16, v10
	v_add3_u32 v11, v11, v12, s0
	v_and_or_b32 v10, v11, s1, v10
	v_mul_f32_e32 v11, v76, v14
	v_mul_f32_e32 v12, v77, v14
	v_bfe_u32 v13, v11, 16, 1
	v_add3_u32 v11, v11, v13, s0
	v_bfe_u32 v13, v12, 16, 1
	v_lshrrev_b32_e32 v11, 16, v11
	v_add3_u32 v12, v12, v13, s0
	v_and_or_b32 v11, v12, s1, v11
	global_store_dwordx2 v[8:9], v[10:11], off offset:512
	v_mul_f32_e32 v10, v62, v14
	v_mul_f32_e32 v11, v63, v14
	v_bfe_u32 v12, v10, 16, 1
	v_add3_u32 v10, v10, v12, s0
	v_bfe_u32 v12, v11, 16, 1
	v_lshrrev_b32_e32 v10, 16, v10
	v_add3_u32 v11, v11, v12, s0
	v_and_or_b32 v10, v11, s1, v10
	v_mul_f32_e32 v11, v64, v14
	v_mul_f32_e32 v12, v65, v14
	v_bfe_u32 v13, v11, 16, 1
	v_add3_u32 v11, v11, v13, s0
	v_bfe_u32 v13, v12, 16, 1
	v_lshrrev_b32_e32 v11, 16, v11
	v_add3_u32 v12, v12, v13, s0
	v_and_or_b32 v11, v12, s1, v11
	global_store_dwordx2 v[8:9], v[10:11], off offset:1024
	v_mul_f32_e32 v10, v90, v14
	v_mul_f32_e32 v11, v91, v14
	v_bfe_u32 v12, v10, 16, 1
	v_add3_u32 v10, v10, v12, s0
	v_bfe_u32 v12, v11, 16, 1
	v_lshrrev_b32_e32 v10, 16, v10
	v_add3_u32 v11, v11, v12, s0
	v_and_or_b32 v10, v11, s1, v10
	v_mul_f32_e32 v11, v92, v14
	v_mul_f32_e32 v12, v93, v14
	v_fmamk_f32 v14, v117, 0x3a800000, v112
	v_bfe_u32 v13, v11, 16, 1
	v_rsq_f32_e32 v14, v14
	v_add3_u32 v11, v11, v13, s0
	v_bfe_u32 v13, v12, 16, 1
	v_lshrrev_b32_e32 v11, 16, v11
	v_add3_u32 v12, v12, v13, s0
	v_and_or_b32 v11, v12, s1, v11
	global_store_dwordx2 v[8:9], v[10:11], off offset:1536
	v_mul_f32_e32 v10, v82, v14
	v_mul_f32_e32 v11, v83, v14
	v_bfe_u32 v12, v10, 16, 1
	v_add3_u32 v10, v10, v12, s0
	v_bfe_u32 v12, v11, 16, 1
	v_lshrrev_b32_e32 v10, 16, v10
	v_add3_u32 v11, v11, v12, s0
	v_and_or_b32 v10, v11, s1, v10
	v_mul_f32_e32 v11, v84, v14
	v_mul_f32_e32 v12, v85, v14
	v_bfe_u32 v13, v11, 16, 1
	v_add3_u32 v11, v11, v13, s0
	v_bfe_u32 v13, v12, 16, 1
	v_lshrrev_b32_e32 v11, 16, v11
	v_add3_u32 v12, v12, v13, s0
	v_and_or_b32 v11, v12, s1, v11
	global_store_dwordx2 v[8:9], v[10:11], off offset:2048
	v_mul_f32_e32 v10, v70, v14
	v_mul_f32_e32 v11, v71, v14
	v_bfe_u32 v12, v10, 16, 1
	v_add3_u32 v10, v10, v12, s0
	v_bfe_u32 v12, v11, 16, 1
	v_lshrrev_b32_e32 v10, 16, v10
	v_add3_u32 v11, v11, v12, s0
	v_and_or_b32 v10, v11, s1, v10
	v_mul_f32_e32 v11, v72, v14
	v_mul_f32_e32 v12, v73, v14
	v_bfe_u32 v13, v11, 16, 1
	v_add3_u32 v11, v11, v13, s0
	v_bfe_u32 v13, v12, 16, 1
	v_lshrrev_b32_e32 v11, 16, v11
	v_add3_u32 v12, v12, v13, s0
	v_and_or_b32 v11, v12, s1, v11
	global_store_dwordx2 v[8:9], v[10:11], off offset:2560
	v_mul_f32_e32 v10, v58, v14
	v_mul_f32_e32 v11, v59, v14
	v_bfe_u32 v12, v10, 16, 1
	v_add3_u32 v10, v10, v12, s0
	v_bfe_u32 v12, v11, 16, 1
	v_lshrrev_b32_e32 v10, 16, v10
	v_add3_u32 v11, v11, v12, s0
	v_and_or_b32 v10, v11, s1, v10
	v_mul_f32_e32 v11, v60, v14
	v_mul_f32_e32 v12, v61, v14
	v_bfe_u32 v13, v11, 16, 1
	v_add3_u32 v11, v11, v13, s0
	v_bfe_u32 v13, v12, 16, 1
	s_waitcnt lgkmcnt(0)
	v_add_f32_e32 v113, v113, v122
	ds_bpermute_b32 v122, v233, v118
	v_lshrrev_b32_e32 v11, 16, v11
	v_add3_u32 v12, v12, v13, s0
	v_and_or_b32 v11, v12, s1, v11
	global_store_dwordx2 v[8:9], v[10:11], off offset:3072
	v_mul_f32_e32 v10, v102, v14
	v_mul_f32_e32 v11, v103, v14
	v_bfe_u32 v12, v10, 16, 1
	v_add3_u32 v10, v10, v12, s0
	v_bfe_u32 v12, v11, 16, 1
	s_waitcnt lgkmcnt(0)
	v_add_f32_e32 v118, v118, v122
	v_lshrrev_b32_e32 v10, 16, v10
	v_add3_u32 v11, v11, v12, s0
	v_and_or_b32 v10, v11, s1, v10
	v_mul_f32_e32 v11, v104, v14
	v_mul_f32_e32 v12, v105, v14
	v_fmamk_f32 v14, v118, 0x3a800000, v112
	v_bfe_u32 v13, v11, 16, 1
	v_rsq_f32_e32 v14, v14
	v_add3_u32 v11, v11, v13, s0
	v_bfe_u32 v13, v12, 16, 1
	v_lshrrev_b32_e32 v11, 16, v11
	v_add3_u32 v12, v12, v13, s0
	v_and_or_b32 v11, v12, s1, v11
	global_store_dwordx2 v[8:9], v[10:11], off offset:3584
	v_mul_f32_e32 v8, v54, v14
	v_mul_f32_e32 v9, v55, v14
	v_bfe_u32 v10, v8, 16, 1
	v_add3_u32 v8, v8, v10, s0
	v_bfe_u32 v10, v9, 16, 1
	v_lshrrev_b32_e32 v8, 16, v8
	v_add3_u32 v9, v9, v10, s0
	v_and_or_b32 v8, v9, s1, v8
	v_mul_f32_e32 v9, v56, v14
	v_mul_f32_e32 v10, v57, v14
	v_bfe_u32 v11, v9, 16, 1
	v_add3_u32 v9, v9, v11, s0
	v_bfe_u32 v11, v10, 16, 1
	v_lshrrev_b32_e32 v9, 16, v9
	v_add3_u32 v10, v10, v11, s0
	v_and_or_b32 v9, v10, s1, v9
	global_store_dwordx2 v[6:7], v[8:9], off
	v_mul_f32_e32 v8, v50, v14
	v_mul_f32_e32 v9, v51, v14
	v_bfe_u32 v10, v8, 16, 1
	v_add3_u32 v8, v8, v10, s0
	v_bfe_u32 v10, v9, 16, 1
	v_lshrrev_b32_e32 v8, 16, v8
	v_add3_u32 v9, v9, v10, s0
	v_and_or_b32 v8, v9, s1, v8
	v_mul_f32_e32 v9, v52, v14
	v_mul_f32_e32 v10, v53, v14
	v_bfe_u32 v11, v9, 16, 1
	v_add3_u32 v9, v9, v11, s0
	v_bfe_u32 v11, v10, 16, 1
	v_lshrrev_b32_e32 v9, 16, v9
	v_add3_u32 v10, v10, v11, s0
	v_and_or_b32 v9, v10, s1, v9
	global_store_dwordx2 v[6:7], v[8:9], off offset:512
	v_mul_f32_e32 v8, v98, v14
	v_mul_f32_e32 v9, v99, v14
	v_bfe_u32 v10, v8, 16, 1
	v_add3_u32 v8, v8, v10, s0
	v_bfe_u32 v10, v9, 16, 1
	v_lshrrev_b32_e32 v8, 16, v8
	v_add3_u32 v9, v9, v10, s0
	v_and_or_b32 v8, v9, s1, v8
	v_mul_f32_e32 v9, v100, v14
	v_mul_f32_e32 v10, v101, v14
	v_bfe_u32 v11, v9, 16, 1
	v_add3_u32 v9, v9, v11, s0
	v_bfe_u32 v11, v10, 16, 1
	ds_bpermute_b32 v123, v233, v113
	v_lshrrev_b32_e32 v9, 16, v9
	v_add3_u32 v10, v10, v11, s0
	v_and_or_b32 v9, v10, s1, v9
	global_store_dwordx2 v[6:7], v[8:9], off offset:1024
	v_mul_f32_e32 v8, v94, v14
	v_mul_f32_e32 v9, v95, v14
	v_bfe_u32 v10, v8, 16, 1
	v_add3_u32 v8, v8, v10, s0
	v_bfe_u32 v10, v9, 16, 1
	s_waitcnt lgkmcnt(0)
	v_add_f32_e32 v113, v113, v123
	v_lshrrev_b32_e32 v8, 16, v8
	v_add3_u32 v9, v9, v10, s0
	v_and_or_b32 v8, v9, s1, v8
	v_mul_f32_e32 v9, v96, v14
	v_fmac_f32_e32 v112, 0x3a800000, v113
	v_mul_f32_e32 v10, v97, v14
	v_bfe_u32 v11, v9, 16, 1
	v_rsq_f32_e32 v12, v112
	v_add3_u32 v9, v9, v11, s0
	v_bfe_u32 v11, v10, 16, 1
	v_lshrrev_b32_e32 v9, 16, v9
	v_add3_u32 v10, v10, v11, s0
	v_and_or_b32 v9, v10, s1, v9
	global_store_dwordx2 v[6:7], v[8:9], off offset:1536
	v_mul_f32_e32 v8, v86, v12
	v_mul_f32_e32 v9, v87, v12
	v_bfe_u32 v10, v8, 16, 1
	v_add3_u32 v8, v8, v10, s0
	v_bfe_u32 v10, v9, 16, 1
	v_lshrrev_b32_e32 v8, 16, v8
	v_add3_u32 v9, v9, v10, s0
	v_and_or_b32 v8, v9, s1, v8
	v_mul_f32_e32 v9, v88, v12
	v_mul_f32_e32 v10, v89, v12
	v_bfe_u32 v11, v9, 16, 1
	v_add3_u32 v9, v9, v11, s0
	v_bfe_u32 v11, v10, 16, 1
	v_lshrrev_b32_e32 v9, 16, v9
	v_add3_u32 v10, v10, v11, s0
	v_and_or_b32 v9, v10, s1, v9
	global_store_dwordx2 v[6:7], v[8:9], off offset:2048
	v_mul_f32_e32 v8, v78, v12
	v_mul_f32_e32 v9, v79, v12
	v_bfe_u32 v10, v8, 16, 1
	v_add3_u32 v8, v8, v10, s0
	v_bfe_u32 v10, v9, 16, 1
	v_lshrrev_b32_e32 v8, 16, v8
	v_add3_u32 v9, v9, v10, s0
	v_and_or_b32 v8, v9, s1, v8
	v_mul_f32_e32 v9, v80, v12
	v_mul_f32_e32 v10, v81, v12
	v_bfe_u32 v11, v9, 16, 1
	v_add3_u32 v9, v9, v11, s0
	v_bfe_u32 v11, v10, 16, 1
	v_lshrrev_b32_e32 v9, 16, v9
	v_add3_u32 v10, v10, v11, s0
	v_and_or_b32 v9, v10, s1, v9
	global_store_dwordx2 v[6:7], v[8:9], off offset:2560
	v_mul_f32_e32 v8, v66, v12
	v_mul_f32_e32 v9, v67, v12
	v_bfe_u32 v10, v8, 16, 1
	v_add3_u32 v8, v8, v10, s0
	v_bfe_u32 v10, v9, 16, 1
	v_lshrrev_b32_e32 v8, 16, v8
	v_add3_u32 v9, v9, v10, s0
	v_and_or_b32 v8, v9, s1, v8
	v_mul_f32_e32 v9, v68, v12
	v_mul_f32_e32 v10, v69, v12
	v_bfe_u32 v11, v9, 16, 1
	v_add3_u32 v9, v9, v11, s0
	v_bfe_u32 v11, v10, 16, 1
	v_lshrrev_b32_e32 v9, 16, v9
	v_add3_u32 v10, v10, v11, s0
	v_and_or_b32 v9, v10, s1, v9
	v_mul_f32_e32 v2, v2, v12
	global_store_dwordx2 v[6:7], v[8:9], off offset:3072
	v_mul_f32_e32 v3, v3, v12
	v_bfe_u32 v8, v2, 16, 1
	v_add3_u32 v2, v2, v8, s0
	v_bfe_u32 v8, v3, 16, 1
	v_lshrrev_b32_e32 v2, 16, v2
	v_add3_u32 v3, v3, v8, s0
	v_and_or_b32 v2, v3, s1, v2
	v_mul_f32_e32 v3, v4, v12
	v_mul_f32_e32 v4, v5, v12
	v_bfe_u32 v5, v3, 16, 1
	v_add3_u32 v3, v3, v5, s0
	v_bfe_u32 v5, v4, 16, 1
	v_lshrrev_b32_e32 v3, 16, v3
	v_add3_u32 v4, v4, v5, s0
	v_and_or_b32 v3, v4, s1, v3
	global_store_dwordx2 v[6:7], v[2:3], off offset:3584
	s_waitcnt vmcnt(0)
	s_barrier
	s_and_saveexec_b64 s[0:1], s[68:69]
	s_cbranch_execz .LBB0_67
	s_mov_b64 s[2:3], exec
	v_mbcnt_lo_u32_b32 v2, s2, 0
	v_mbcnt_hi_u32_b32 v2, s3, v2
	v_cmp_eq_u32_e32 vcc, 0, v2
	s_and_b64 s[4:5], exec, vcc
	s_mov_b64 exec, s[4:5]
	s_cbranch_execz .LBB0_67
	s_bcnt1_i32_b64 s2, s[2:3]
	v_mov_b32_e32 v2, 0x1000000
	v_mov_b32_e32 v3, s2
	global_atomic_add v2, v3, s[10:11] offset:768
